# ret_out: coalesced prefetch of the gate tile at item start (row-per-lane gate loads behind the reduction barrier then hit in cache), on top of s_prev/k/v LDS staging
# speedup vs baseline: 1.0174x; 1.0015x over previous
.LBB0_913:
	s_or_b64 exec, exec, s[0:1]
	v_readlane_b32 s20, v253, 13
	v_readlane_b32 s21, v253, 14
	v_ashrrev_i32_e32 v201, 31, v10
	v_mov_b32_e32 v200, v10
	v_lshlrev_b64 v[200:201], 15, v[200:201]
	v_lshlrev_b32_e32 v202, 4, v172
	v_mov_b32_e32 v203, 0
	v_lshl_add_u64 v[200:201], s[20:21], 0, v[200:201]
	v_lshl_add_u64 v[232:233], v[200:201], 0, v[202:203]
	s_mov_b64 s[20:21], 0x1000
	global_load_dwordx4 v[200:203], v[232:233], off
	v_lshl_add_u64 v[232:233], v[232:233], 0, s[20:21]
	global_load_dwordx4 v[204:207], v[232:233], off
	v_lshl_add_u64 v[232:233], v[232:233], 0, s[20:21]
	global_load_dwordx4 v[208:211], v[232:233], off
	v_lshl_add_u64 v[232:233], v[232:233], 0, s[20:21]
	global_load_dwordx4 v[212:215], v[232:233], off
	v_lshl_add_u64 v[232:233], v[232:233], 0, s[20:21]
	global_load_dwordx4 v[216:219], v[232:233], off
	v_lshl_add_u64 v[232:233], v[232:233], 0, s[20:21]
	global_load_dwordx4 v[220:223], v[232:233], off
	v_lshl_add_u64 v[232:233], v[232:233], 0, s[20:21]
	global_load_dwordx4 v[224:227], v[232:233], off
	v_lshl_add_u64 v[232:233], v[232:233], 0, s[20:21]
	global_load_dwordx4 v[228:231], v[232:233], off
	v_and_b32_e32 v169, 3, v2
	v_cvt_f32_ubyte0_e32 v0, v169
	v_sub_f32_e32 v0, 0xc0a00000, v0
	v_cmp_gt_f32_e32 vcc, s34, v0
	s_mov_b32 s0, 0x3f2aaaab
	v_and_b32_e32 v113, 31, v172
	v_cndmask_b32_e32 v2, 0, v187, vcc
	v_add_f32_e32 v0, v0, v2
	v_exp_f32_e32 v0, v0
	v_cndmask_b32_e32 v2, 0, v188, vcc
	v_ashrrev_i32_e32 v191, 1, v172
	v_and_or_b32 v193, v191, 32, v113
	v_ldexp_f32 v11, v0, v2
	v_sub_f32_e32 v0, 1.0, v11
	v_add_f32_e32 v2, -1.0, v0
	v_sub_f32_e32 v3, v2, v0
	v_add_f32_e32 v3, 1.0, v3
	v_sub_f32_e64 v2, -v11, v2
	v_add_f32_e32 v4, v2, v3
	v_frexp_mant_f32_e32 v5, v0
	v_cvt_f64_f32_e32 v[2:3], v0
	v_frexp_exp_i32_f64_e32 v2, v[2:3]
	v_cmp_gt_f32_e32 vcc, s0, v5
	v_readlane_b32 s0, v252, 55
	v_readlane_b32 s1, v252, 56
	v_subbrev_co_u32_e32 v111, vcc, 0, v2, vcc
	v_sub_u32_e32 v2, 0, v111
	v_ldexp_f32 v0, v0, v2
	v_ldexp_f32 v2, v4, v2
	v_add_f32_e32 v4, -1.0, v0
	v_add_f32_e32 v3, 1.0, v4
	v_sub_f32_e32 v3, v0, v3
	v_add_f32_e32 v5, v2, v3
	v_add_f32_e32 v3, 1.0, v0
	v_add_f32_e32 v6, -1.0, v3
	v_sub_f32_e32 v0, v0, v6
	v_add_f32_e32 v0, v2, v0
	v_add_f32_e32 v114, v3, v0
	v_rcp_f32_e32 v116, v114
	v_sub_f32_e32 v2, v114, v3
	v_add_f32_e32 v3, v4, v5
	v_sub_f32_e32 v115, v0, v2
	v_mul_f32_e32 v117, v3, v116
	v_mul_f32_e32 v18, v114, v117
	v_sub_f32_e32 v0, v3, v4
	v_fma_f32 v4, v117, v114, -v18
	v_fmac_f32_e32 v4, v117, v115
	v_add_f32_e32 v2, v18, v4
	v_sub_f32_e32 v19, v3, v2
	v_sub_f32_e32 v0, v5, v0
	v_pk_add_f32 v[6:7], v[2:3], v[18:19] neg_lo:[0,1] neg_hi:[0,1]
	v_mov_b32_e32 v5, v2
	v_pk_add_f32 v[2:3], v[6:7], v[4:5] neg_lo:[0,1] neg_hi:[0,1]
	v_bfe_u32 v173, v172, 5, 1
	v_add_f32_e32 v0, v0, v3
	v_add_f32_e32 v18, v2, v0
	v_add_u32_e32 v2, v112, v193
	v_ashrrev_i32_e32 v3, 31, v2
	v_lshlrev_b64 v[174:175], 10, v[2:3]
	v_lshl_add_u64 v[2:3], s[0:1], 0, v[174:175]
	v_lshlrev_b32_e32 v0, 8, v169
	v_lshl_add_u64 v[2:3], v[2:3], 0, v[0:1]
	v_lshlrev_b32_e32 v32, 4, v173
	v_mov_b32_e32 v33, v1
	v_lshl_add_u64 v[2:3], v[2:3], 0, v[32:33]
	global_load_dwordx4 v[78:81], v[2:3], off
	global_load_dwordx4 v[74:77], v[2:3], off offset:32
	global_load_dwordx4 v[70:73], v[2:3], off offset:64
	global_load_dwordx4 v[66:69], v[2:3], off offset:96
	global_load_dwordx4 v[62:65], v[2:3], off offset:128
	global_load_dwordx4 v[58:61], v[2:3], off offset:160
	global_load_dwordx4 v[54:57], v[2:3], off offset:192
	global_load_dwordx4 v[50:53], v[2:3], off offset:224
	v_add_u32_e32 v2, v112, v113
	v_ashrrev_i32_e32 v3, 31, v2
	v_readlane_b32 s20, v252, 53
	v_lshlrev_b64 v[2:3], 10, v[2:3]
	v_readlane_b32 s21, v252, 54
	v_and_b32_e32 v192, 0xffffffc0, v191
	v_lshlrev_b32_e32 v16, 1, v16
	v_mov_b32_e32 v17, v1
	v_lshlrev_b32_e32 v20, 3, v173
	v_mov_b32_e32 v21, v1
	v_lshl_add_u64 v[2:3], s[20:21], 0, v[2:3]
	v_or_b32_e32 v110, v192, v113
	v_lshl_add_u64 v[12:13], v[12:13], 0, v[16:17]
	v_mov_b64_e32 v[248:249], v[12:13]
	v_lshl_add_u64 v[2:3], v[2:3], 0, v[0:1]
	v_lshl_add_u64 v[12:13], v[12:13], 0, v[20:21]
	v_mad_i64_i32 v[16:17], s[0:1], v14, v110, 0
	v_lshl_add_u64 v[22:23], v[2:3], 0, v[32:33]
	v_lshl_add_u64 v[16:17], v[16:17], 1, v[12:13]
	v_lshrrev_b32_e32 v232, 4, v172
	v_add_u32_e32 v232, v112, v232
	v_ashrrev_i32_e32 v233, 31, v232
	v_lshlrev_b64 v[232:233], 10, v[232:233]
	v_and_b32_e32 v254, 15, v172
	v_lshlrev_b32_e32 v254, 4, v254
	v_mov_b32_e32 v255, 0
	v_lshl_add_u64 v[232:233], s[20:21], 0, v[232:233]
	v_lshl_add_u64 v[232:233], v[232:233], 0, v[0:1]
	v_lshl_add_u64 v[232:233], v[232:233], 0, v[254:255]
	s_mov_b64 s[20:21], 0x4000
	global_load_dwordx4 v[46:49], v[232:233], off
	v_lshl_add_u64 v[232:233], v[232:233], 0, s[20:21]
	global_load_dwordx4 v[42:45], v[232:233], off
	v_lshl_add_u64 v[232:233], v[232:233], 0, s[20:21]
	global_load_dwordx4 v[38:41], v[232:233], off
	v_lshl_add_u64 v[232:233], v[232:233], 0, s[20:21]
	global_load_dwordx4 v[28:31], v[232:233], off
	v_mul_u32_u24_e32 v242, 0x90, v110
	v_add3_u32 v242, v242, v20, v182
	v_add_u32_e32 v242, 0xd400, v242
	v_add_u32_e32 v243, 0x1200, v242
	v_lshrrev_b32_e32 v246, 3, v172
	v_mad_i64_i32 v[244:245], s[0:1], v14, v246, 0
	v_and_b32_e32 v246, 7, v172
	v_lshlrev_b32_e32 v246, 4, v246
	v_mov_b32_e32 v247, 0
	v_lshl_add_u64 v[244:245], v[244:245], 1, v[248:249]
	v_lshl_add_u64 v[244:245], v[244:245], 0, v[246:247]
	v_lshlrev_b32_e32 v246, 6, v14
	global_load_dwordx4 v[94:97], v[244:245], off
	v_lshl_add_u64 v[244:245], v[244:245], 0, v[246:247]
	global_load_dwordx4 v[90:93], v[244:245], off
	v_lshl_add_u64 v[244:245], v[244:245], 0, v[246:247]
	global_load_dwordx4 v[86:89], v[244:245], off
	v_lshl_add_u64 v[244:245], v[244:245], 0, v[246:247]
	global_load_dwordx4 v[82:85], v[244:245], off
	v_lshrrev_b32_e32 v244, 4, v172
	v_add_u32_e32 v244, v112, v244
	v_ashrrev_i32_e32 v245, 31, v244
	v_lshlrev_b64 v[244:245], 11, v[244:245]
	v_lshlrev_b32_e32 v246, 8, v169
	v_mov_b32_e32 v247, 0
	v_lshl_add_u64 v[244:245], s[10:11], 0, v[244:245]
	v_lshl_add_u64 v[244:245], v[244:245], 0, v[246:247]
	v_and_b32_e32 v246, 15, v172
	v_lshlrev_b32_e32 v246, 4, v246
	v_lshl_add_u64 v[244:245], v[244:245], 0, v[246:247]
	v_mov_b32_e32 v246, 0x8000
	global_load_dwordx4 v[34:37], v[244:245], off
	v_lshl_add_u64 v[244:245], v[244:245], 0, v[246:247]
	global_load_dwordx4 v[106:109], v[244:245], off
	v_lshl_add_u64 v[244:245], v[244:245], 0, v[246:247]
	global_load_dwordx4 v[102:105], v[244:245], off
	v_lshl_add_u64 v[244:245], v[244:245], 0, v[246:247]
	global_load_dwordx4 v[98:101], v[244:245], off
	v_add_f32_e32 v15, v19, v18
	v_mul_f32_e32 v118, v116, v15
	v_mul_f32_e32 v12, v114, v118
	v_fma_f32 v16, v118, v114, -v12
	v_fmac_f32_e32 v16, v118, v115
	v_sub_f32_e32 v13, v19, v15
	v_add_f32_e32 v14, v12, v16
	v_add_f32_e32 v20, v18, v13
	v_sub_f32_e32 v13, v15, v14
	v_pk_add_f32 v[18:19], v[14:15], v[12:13] neg_lo:[0,1] neg_hi:[0,1]
	v_mov_b32_e32 v17, v14
	v_pk_add_f32 v[14:15], v[18:19], v[16:17] neg_lo:[0,1] neg_hi:[0,1]
	s_mov_b32 s0, 0x3f317218
	v_add_f32_e32 v12, v20, v15
	v_add_f32_e32 v12, v14, v12
	v_add_f32_e32 v12, v13, v12
	v_add_f32_e32 v13, v117, v118
	v_sub_f32_e32 v14, v13, v117
	v_mul_f32_e32 v12, v116, v12
	v_sub_f32_e32 v14, v118, v14
	v_add_f32_e32 v14, v14, v12
	v_add_f32_e32 v16, v13, v14
	v_mul_f32_e32 v17, v16, v16
	v_fmamk_f32 v12, v17, 0x3e9b6dac, v185
	v_fmaak_f32 v171, v17, v12, 0x3f2aaada
	v_cvt_f32_i32_e32 v12, v111
	v_sub_f32_e32 v13, v16, v13
	v_sub_f32_e32 v13, v14, v13
	v_ldexp_f32 v18, v13, 1
	v_mul_f32_e32 v13, v16, v17
	v_ldexp_f32 v15, v16, 1
	v_pk_mul_f32 v[16:17], v[12:13], v[170:171]
	v_cmp_nlt_f32_e32 vcc, 1.0, v11
	v_fma_f32 v14, v12, s0, -v16
	v_fmac_f32_e32 v14, 0xb102e308, v12
	v_pk_add_f32 v[12:13], v[16:17], v[14:15]
	s_mov_b32 s0, 0x33800000
	v_sub_f32_e32 v15, v13, v15
	v_sub_f32_e32 v15, v17, v15
	v_add_f32_e32 v19, v18, v15
	v_mov_b32_e32 v18, v16
	v_pk_add_f32 v[16:17], v[12:13], v[16:17] neg_lo:[0,1] neg_hi:[0,1]
	v_pk_add_f32 v[20:21], v[12:13], v[18:19]
	v_mov_b32_e32 v15, v12
	v_mov_b32_e32 v17, v21
	v_pk_add_f32 v[22:23], v[14:15], v[16:17] neg_lo:[0,1] neg_hi:[0,1]
	v_pk_add_f32 v[14:15], v[14:15], v[16:17]
	v_mov_b32_e32 v18, v19
	v_pk_add_f32 v[16:17], v[14:15], v[12:13] op_sel:[1,0] op_sel_hi:[0,1] neg_lo:[0,1] neg_hi:[0,1]
	v_pk_add_f32 v[114:115], v[20:21], v[16:17] op_sel_hi:[1,0] neg_lo:[0,1] neg_hi:[0,1]
	v_mov_b32_e32 v20, v21
	v_mov_b32_e32 v21, v15
	v_pk_mov_b32 v[16:17], v[12:13], v[16:17] op_sel:[1,0]
	v_mov_b32_e32 v19, v12
	v_pk_add_f32 v[16:17], v[20:21], v[16:17] neg_lo:[0,1] neg_hi:[0,1]
	v_mov_b32_e32 v114, v22
	v_pk_add_f32 v[12:13], v[18:19], v[16:17] neg_lo:[0,1] neg_hi:[0,1]
	v_mov_b32_e32 v23, v15
	v_pk_add_f32 v[16:17], v[114:115], v[12:13]
	v_lshlrev_b32_e32 v171, 2, v173
	v_pk_add_f32 v[18:19], v[16:17], v[16:17] op_sel:[0,1] op_sel_hi:[1,0]
	v_ashrrev_i32_e32 v111, 31, v110
	v_pk_add_f32 v[14:15], v[14:15], v[18:19] op_sel:[1,0] op_sel_hi:[0,1]
	v_mov_b32_e32 v17, v14
	v_pk_add_f32 v[20:21], v[16:17], v[22:23] neg_lo:[0,1] neg_hi:[0,1]
	v_mov_b32_e32 v13, v18
	v_sub_f32_e32 v15, v16, v20
	v_pk_add_f32 v[12:13], v[12:13], v[20:21] neg_lo:[0,1] neg_hi:[0,1]
	v_sub_f32_e32 v15, v22, v15
	v_add_f32_e32 v12, v12, v15
	v_add_f32_e32 v12, v12, v13
	v_add_f32_e32 v12, v14, v12
	v_cndmask_b32_e32 v12, v189, v12, vcc
	v_cmp_neq_f32_e32 vcc, 1.0, v11
	s_nop 1
	v_cndmask_b32_e32 v12, v190, v12, vcc
	v_cmp_gt_f32_e32 vcc, s0, v11
	v_readlane_b32 s0, v253, 13
	v_readlane_b32 s1, v253, 14
	v_cndmask_b32_e64 v11, v12, -v11, vcc
	v_mul_f32_e32 v194, 0x3fb8aa3b, v11
	v_ashrrev_i32_e32 v11, 31, v10
	v_lshlrev_b64 v[10:11], 15, v[10:11]
	v_lshl_add_u64 v[154:155], s[0:1], 0, v[10:11]
	s_waitcnt vmcnt(0)
	v_lshrrev_b32_e32 v232, 4, v172
	v_and_b32_e32 v233, 15, v172
	v_mul_u32_u24_e32 v232, 0x110, v232
	v_lshl_add_u32 v232, v233, 4, v232
	v_add_u32_e32 v232, v232, v182
	v_mul_u32_u24_e32 v241, 0x110, v113
	v_add3_u32 v241, v241, v32, v182
	v_add_u32_e32 v232, 0x9000, v232
	v_add_u32_e32 v241, 0x9000, v241
	ds_write_b128 v232, v[46:49]
	ds_write_b128 v232, v[42:45] offset:4352
	ds_write_b128 v232, v[38:41] offset:8704
	ds_write_b128 v232, v[28:31] offset:13056
	v_lshrrev_b32_e32 v233, 3, v172
	v_and_b32_e32 v244, 7, v172
	v_mul_u32_u24_e32 v233, 0x90, v233
	v_lshl_add_u32 v233, v244, 4, v233
	v_add_u32_e32 v233, v233, v182
	v_add_u32_e32 v233, 0xd400, v233
	ds_write_b128 v233, v[94:97]
	ds_write_b128 v233, v[90:93] offset:4608
	ds_write_b128 v233, v[86:89] offset:9216
	ds_write_b128 v233, v[82:85] offset:13824
	s_waitcnt lgkmcnt(0)
	s_barrier
	ds_read_b128 v[6:9], v241
	ds_read_b128 v[46:49], v241 offset:32
	ds_read_b128 v[42:45], v241 offset:64
	ds_read_b128 v[38:41], v241 offset:96
	ds_read_b128 v[28:31], v241 offset:128
	ds_read_b128 v[2:5], v241 offset:160
	ds_read_b128 v[24:27], v241 offset:192
	ds_read_b128 v[150:153], v241 offset:224
	s_waitcnt lgkmcnt(0)
	v_mfma_f32_32x32x16_bf16 v[8:23], v[6:9], v[78:81], 0
	v_or_b32_e32 v195, 32, v113
	v_lshlrev_b64 v[6:7], 8, v[110:111]
	v_lshl_add_u64 v[6:7], v[154:155], 0, v[6:7]
	v_lshl_add_u64 v[6:7], v[6:7], 0, v[32:33]
	s_nop 0
	v_mfma_f32_32x32x16_bf16 v[8:23], v[46:49], v[74:77], v[8:23]
	s_nop 0
	v_mfma_f32_32x32x16_bf16 v[8:23], v[42:45], v[70:73], v[8:23]
	s_nop 0
	v_mfma_f32_32x32x16_bf16 v[8:23], v[38:41], v[66:69], v[8:23]
	s_nop 0
	v_mfma_f32_32x32x16_bf16 v[8:23], v[28:31], v[62:65], v[8:23]
	v_add_u32_e32 v28, v112, v195
	v_ashrrev_i32_e32 v29, 31, v28
	v_lshlrev_b64 v[28:29], 10, v[28:29]
	v_lshl_add_u64 v[28:29], s[20:21], 0, v[28:29]
	v_lshl_add_u64 v[28:29], v[28:29], 0, v[0:1]
	v_lshl_add_u64 v[28:29], v[28:29], 0, v[32:33]
	s_nop 0
	v_mfma_f32_32x32x16_bf16 v[8:23], v[2:5], v[58:61], v[8:23]
	ds_read_b128 v[2:5], v241 offset:8704
	ds_read_b128 v[146:149], v241 offset:8736
	ds_read_b128 v[142:145], v241 offset:8768
	ds_read_b128 v[138:141], v241 offset:8800
	ds_read_b128 v[130:133], v241 offset:8832
	ds_read_b128 v[126:129], v241 offset:8864
	ds_read_b128 v[134:137], v241 offset:8896
	s_nop 0
	ds_read_b128 v[28:31], v241 offset:8928
	s_nop 0
	v_mfma_f32_32x32x16_bf16 v[8:23], v[24:27], v[54:57], v[8:23]
	s_waitcnt vmcnt(16)
	v_lshrrev_b32_e32 v232, 4, v172
	v_and_b32_e32 v233, 15, v172
	v_mul_u32_u24_e32 v232, 0x110, v232
	v_lshl_add_u32 v232, v233, 4, v232
	v_add_u32_e32 v232, v232, v182
	v_mul_u32_u24_e32 v233, 0x110, v110
	v_add3_u32 v233, v233, v32, v182
	v_add_u32_e32 v232, 0x800, v232
	v_add_u32_e32 v233, 0x800, v233
	ds_write_b128 v232, v[200:203]
	ds_write_b128 v232, v[204:207] offset:4352
	ds_write_b128 v232, v[208:211] offset:8704
	ds_write_b128 v232, v[212:215] offset:13056
	ds_write_b128 v232, v[216:219] offset:17408
	ds_write_b128 v232, v[220:223] offset:21760
	ds_write_b128 v232, v[224:227] offset:26112
	ds_write_b128 v232, v[228:231] offset:30464
	s_waitcnt lgkmcnt(0)
	s_barrier
	ds_read_b128 v[24:27], v233
	ds_read_b128 v[122:125], v233 offset:32
	ds_read_b128 v[118:121], v233 offset:64
	ds_read_b128 v[114:117], v233 offset:96
	ds_read_b128 v[110:113], v233 offset:128
	ds_read_b128 v[46:49], v233 offset:160
	ds_read_b128 v[42:45], v233 offset:192
	ds_read_b128 v[38:41], v233 offset:224
	s_nop 0
	v_mfma_f32_32x32x16_bf16 v[8:23], v[150:153], v[50:53], v[8:23]
	v_min_u32_e32 v0, v171, v193
	v_max_u32_e32 v6, v171, v193
	v_sub_u32_e32 v0, v6, v0
	v_cvt_f32_u32_e32 v0, v0
	v_or_b32_e32 v6, 1, v171
	v_mul_f32_e32 v7, v194, v0
	v_cmp_gt_f32_e32 vcc, s34, v7
	s_nop 1
	v_cndmask_b32_e32 v7, 0, v187, vcc
	v_fmac_f32_e32 v7, v194, v0
	v_exp_f32_e32 v0, v7
	v_min_u32_e32 v7, v6, v193
	v_max_u32_e32 v6, v6, v193
	v_sub_u32_e32 v6, v6, v7
	v_cvt_f32_u32_e32 v7, v6
	v_cndmask_b32_e32 v6, 0, v188, vcc
	v_ldexp_f32 v6, v0, v6
	v_mul_f32_e32 v0, v194, v7
	v_cmp_gt_f32_e32 vcc, s34, v0
	s_nop 1
	v_cndmask_b32_e32 v0, 0, v187, vcc
	v_fmac_f32_e32 v0, v194, v7
	v_exp_f32_e32 v0, v0
	v_or_b32_e32 v7, 2, v171
	v_min_u32_e32 v150, v7, v193
	v_max_u32_e32 v7, v7, v193
	v_sub_u32_e32 v7, v7, v150
	v_cvt_f32_u32_e32 v152, v7
	v_cndmask_b32_e32 v7, 0, v188, vcc
	v_ldexp_f32 v7, v0, v7
	v_pk_mul_f32 v[150:151], v[8:9], v[6:7]
	v_or_b32_e32 v6, 3, v171
	v_min_u32_e32 v7, v6, v193
	v_max_u32_e32 v6, v6, v193
	v_sub_u32_e32 v6, v6, v7
	v_cvt_f32_u32_e32 v6, v6
	v_mul_f32_e32 v0, v194, v152
	v_cmp_gt_f32_e32 vcc, s34, v0
	v_mul_f32_e32 v8, v194, v6
	s_nop 0
	v_cndmask_b32_e32 v0, 0, v187, vcc
	v_cndmask_b32_e32 v7, 0, v188, vcc
	v_cmp_gt_f32_e32 vcc, s34, v8
	v_fmac_f32_e32 v0, v194, v152
	v_exp_f32_e32 v0, v0
	v_cndmask_b32_e32 v8, 0, v187, vcc
	v_fmac_f32_e32 v8, v194, v6
	v_or_b32_e32 v6, 8, v171
	v_min_u32_e32 v9, v6, v193
	v_max_u32_e32 v6, v6, v193
	v_sub_u32_e32 v6, v6, v9
	v_exp_f32_e32 v8, v8
	v_cvt_f32_u32_e32 v9, v6
	v_ldexp_f32 v6, v0, v7
	v_cndmask_b32_e32 v0, 0, v188, vcc
	v_ldexp_f32 v7, v8, v0
	v_mul_f32_e32 v0, v194, v9
	v_cmp_gt_f32_e32 vcc, s34, v0
	v_or_b32_e32 v8, 9, v171
	v_pk_mul_f32 v[152:153], v[10:11], v[6:7]
	v_cndmask_b32_e32 v0, 0, v187, vcc
	v_fmac_f32_e32 v0, v194, v9
	v_min_u32_e32 v9, v8, v193
	v_max_u32_e32 v8, v8, v193
	v_sub_u32_e32 v8, v8, v9
	v_exp_f32_e32 v0, v0
	v_cvt_f32_u32_e32 v8, v8
	v_cndmask_b32_e32 v6, 0, v188, vcc
	v_or_b32_e32 v7, 10, v171
	v_ldexp_f32 v6, v0, v6
	v_mul_f32_e32 v0, v194, v8
	v_cmp_gt_f32_e32 vcc, s34, v0
	s_nop 1
	v_cndmask_b32_e32 v0, 0, v187, vcc
	v_fmac_f32_e32 v0, v194, v8
	v_exp_f32_e32 v0, v0
	v_min_u32_e32 v8, v7, v193
	v_max_u32_e32 v7, v7, v193
	v_sub_u32_e32 v7, v7, v8
	v_cvt_f32_u32_e32 v8, v7
	v_cndmask_b32_e32 v7, 0, v188, vcc
	v_ldexp_f32 v7, v0, v7
	v_pk_mul_f32 v[156:157], v[12:13], v[6:7]
	v_or_b32_e32 v6, 11, v171
	v_min_u32_e32 v7, v6, v193
	v_max_u32_e32 v6, v6, v193
	v_sub_u32_e32 v6, v6, v7
	v_cvt_f32_u32_e32 v6, v6
	v_mul_f32_e32 v0, v194, v8
	v_cmp_gt_f32_e32 vcc, s34, v0
	s_nop 1
	v_cndmask_b32_e32 v0, 0, v187, vcc
	v_fmac_f32_e32 v0, v194, v8
	v_mul_f32_e32 v8, v194, v6
	v_cndmask_b32_e32 v7, 0, v188, vcc
	v_cmp_gt_f32_e32 vcc, s34, v8
	v_exp_f32_e32 v0, v0
	s_nop 0
	v_cndmask_b32_e32 v8, 0, v187, vcc
	v_fmac_f32_e32 v8, v194, v6
	v_or_b32_e32 v6, 16, v171
	v_min_u32_e32 v9, v6, v193
	v_max_u32_e32 v6, v6, v193
	v_sub_u32_e32 v6, v6, v9
	v_exp_f32_e32 v8, v8
	v_cvt_f32_u32_e32 v9, v6
	v_ldexp_f32 v6, v0, v7
	v_cndmask_b32_e32 v0, 0, v188, vcc
	v_ldexp_f32 v7, v8, v0
	v_mul_f32_e32 v0, v194, v9
	v_cmp_gt_f32_e32 vcc, s34, v0
	v_or_b32_e32 v8, 17, v171
	v_pk_mul_f32 v[158:159], v[14:15], v[6:7]
	v_cndmask_b32_e32 v0, 0, v187, vcc
	v_fmac_f32_e32 v0, v194, v9
	v_min_u32_e32 v9, v8, v193
	v_max_u32_e32 v8, v8, v193
	v_sub_u32_e32 v8, v8, v9
	v_exp_f32_e32 v0, v0
	v_cvt_f32_u32_e32 v8, v8
	v_cndmask_b32_e32 v6, 0, v188, vcc
	v_or_b32_e32 v7, 18, v171
	v_ldexp_f32 v6, v0, v6
	v_mul_f32_e32 v0, v194, v8
	v_cmp_gt_f32_e32 vcc, s34, v0
	s_nop 1
	v_cndmask_b32_e32 v0, 0, v187, vcc
	v_fmac_f32_e32 v0, v194, v8
	v_exp_f32_e32 v0, v0
	v_min_u32_e32 v8, v7, v193
	v_max_u32_e32 v7, v7, v193
	v_sub_u32_e32 v7, v7, v8
	v_cvt_f32_u32_e32 v8, v7
	v_cndmask_b32_e32 v7, 0, v188, vcc
	v_ldexp_f32 v7, v0, v7
	v_pk_mul_f32 v[160:161], v[16:17], v[6:7]
	v_or_b32_e32 v6, 19, v171
	v_min_u32_e32 v7, v6, v193
	v_max_u32_e32 v6, v6, v193
	v_sub_u32_e32 v6, v6, v7
	v_cvt_f32_u32_e32 v6, v6
	v_mul_f32_e32 v0, v194, v8
	v_cmp_gt_f32_e32 vcc, s34, v0
	s_nop 1
	v_cndmask_b32_e32 v0, 0, v187, vcc
	v_fmac_f32_e32 v0, v194, v8
	v_mul_f32_e32 v8, v194, v6
	v_cndmask_b32_e32 v7, 0, v188, vcc
	v_cmp_gt_f32_e32 vcc, s34, v8
	v_exp_f32_e32 v0, v0
	s_nop 0
	v_cndmask_b32_e32 v8, 0, v187, vcc
	v_fmac_f32_e32 v8, v194, v6
	v_exp_f32_e32 v6, v8
	v_or_b32_e32 v8, 24, v171
	v_min_u32_e32 v9, v8, v193
	v_max_u32_e32 v8, v8, v193
	v_sub_u32_e32 v8, v8, v9
	v_cvt_f32_u32_e32 v8, v8
	v_ldexp_f32 v176, v0, v7
	v_cndmask_b32_e32 v0, 0, v188, vcc
	v_ldexp_f32 v177, v6, v0
	v_mul_f32_e32 v0, v194, v8
	v_cmp_gt_f32_e32 vcc, s34, v0
	v_or_b32_e32 v6, 25, v171
	v_min_u32_e32 v7, v6, v193
	v_cndmask_b32_e32 v0, 0, v187, vcc
	v_max_u32_e32 v6, v6, v193
	v_fmac_f32_e32 v0, v194, v8
	v_sub_u32_e32 v178, v6, v7
	s_nop 0
	v_mfma_f32_32x32x16_bf16 v[2:17], v[2:5], v[78:81], 0
	v_exp_f32_e32 v0, v0
	v_cvt_f32_u32_e32 v178, v178
	v_pk_mul_f32 v[18:19], v[18:19], v[176:177]
	v_cndmask_b32_e32 v176, 0, v188, vcc
	v_ldexp_f32 v176, v0, v176
	v_mul_f32_e32 v0, v194, v178
	v_cmp_gt_f32_e32 vcc, s34, v0
	s_nop 0
	v_mfma_f32_32x32x16_bf16 v[2:17], v[146:149], v[74:77], v[2:17]
	v_or_b32_e32 v146, 26, v171
	v_cndmask_b32_e32 v0, 0, v187, vcc
	v_fmac_f32_e32 v0, v194, v178
	v_exp_f32_e32 v0, v0
	v_min_u32_e32 v147, v146, v193
	v_max_u32_e32 v146, v146, v193
	v_sub_u32_e32 v146, v146, v147
	s_nop 0
	v_mfma_f32_32x32x16_bf16 v[2:17], v[142:145], v[70:73], v[2:17]
	v_cndmask_b32_e32 v142, 0, v188, vcc
	v_ldexp_f32 v177, v0, v142
	v_or_b32_e32 v142, 27, v171
	v_min_u32_e32 v143, v142, v193
	v_max_u32_e32 v142, v142, v193
	v_cvt_f32_u32_e32 v146, v146
	v_pk_mul_f32 v[20:21], v[20:21], v[176:177]
	s_nop 0
	v_mfma_f32_32x32x16_bf16 v[2:17], v[138:141], v[66:69], v[2:17]
	v_sub_u32_e32 v138, v142, v143
	v_cvt_f32_u32_e32 v138, v138
	v_mul_f32_e32 v0, v194, v146
	v_cmp_gt_f32_e32 vcc, s34, v0
	v_mul_f32_e32 v139, v194, v138
	s_nop 0
	v_cndmask_b32_e32 v0, 0, v187, vcc
	s_nop 0
	v_mfma_f32_32x32x16_bf16 v[2:17], v[130:133], v[62:65], v[2:17]
	v_cmp_gt_f32_e64 s[0:1], s34, v139
	v_fmac_f32_e32 v0, v194, v146
	v_exp_f32_e32 v0, v0
	v_cndmask_b32_e64 v130, 0, v187, s[0:1]
	v_fmac_f32_e32 v130, v194, v138
	v_exp_f32_e32 v131, v130
	v_cndmask_b32_e32 v130, 0, v188, vcc
	v_ldexp_f32 v130, v0, v130
	v_cndmask_b32_e64 v0, 0, v188, s[0:1]
	v_ldexp_f32 v131, v131, v0
	v_or_b32_e32 v0, 32, v171
	s_nop 0
	v_mfma_f32_32x32x16_bf16 v[2:17], v[126:129], v[58:61], v[2:17]
	v_cvt_pk_bf16_f32 v127, v18, v19
	v_min_u32_e32 v18, v0, v193
	v_max_u32_e32 v0, v0, v193
	v_sub_u32_e32 v0, v0, v18
	v_cvt_f32_u32_e32 v0, v0
	v_or_b32_e32 v19, 33, v171
	v_cvt_pk_bf16_f32 v128, v20, v21
	v_min_u32_e32 v20, v19, v193
	v_max_u32_e32 v19, v19, v193
	v_sub_u32_e32 v19, v19, v20
	v_cvt_f32_u32_e32 v19, v19
	v_mul_f32_e32 v18, v194, v0
	v_cmp_gt_f32_e32 vcc, s34, v18
	s_nop 0
	v_mfma_f32_32x32x16_bf16 v[2:17], v[134:137], v[54:57], v[2:17]
	v_mul_f32_e32 v20, v194, v19
	v_cndmask_b32_e32 v18, 0, v187, vcc
	v_fmac_f32_e32 v18, v194, v0
	v_exp_f32_e32 v0, v18
	v_cndmask_b32_e32 v18, 0, v188, vcc
	v_cmp_gt_f32_e32 vcc, s34, v20
	v_pk_mul_f32 v[22:23], v[22:23], v[130:131]
	v_ldexp_f32 v18, v0, v18
	v_cndmask_b32_e32 v20, 0, v187, vcc
	v_fmac_f32_e32 v20, v194, v19
	v_exp_f32_e32 v19, v20
	v_or_b32_e32 v20, 34, v171
	v_min_u32_e32 v21, v20, v193
	v_max_u32_e32 v20, v20, v193
	v_sub_u32_e32 v20, v20, v21
	v_cvt_f32_u32_e32 v20, v20
	v_cndmask_b32_e32 v0, 0, v188, vcc
	v_ldexp_f32 v19, v19, v0
	ds_read2_b64 v[34:37], v242 offset1:2
	ds_read2_b64 v[106:109], v242 offset0:4 offset1:6
	ds_read2_b64 v[102:105], v242 offset0:8 offset1:10
	ds_read2_b64 v[98:101], v242 offset0:12 offset1:14
	ds_read2_b64 v[94:97], v243 offset1:2
	ds_read2_b64 v[90:93], v243 offset0:4 offset1:6
	ds_read2_b64 v[86:89], v243 offset0:8 offset1:10
	ds_read2_b64 v[82:85], v243 offset0:12 offset1:14
	v_mfma_f32_32x32x16_bf16 v[2:17], v[28:31], v[50:53], v[2:17]
	v_mul_f32_e32 v0, v194, v20
	v_cmp_gt_f32_e32 vcc, s34, v0
	v_cvt_pk_bf16_f32 v129, v22, v23
	v_cvt_pk_bf16_f32 v130, v150, v151
	v_cndmask_b32_e32 v0, 0, v187, vcc
	v_fmac_f32_e32 v0, v194, v20
	v_or_b32_e32 v20, 35, v171
	v_min_u32_e32 v21, v20, v193
	v_max_u32_e32 v20, v20, v193
	v_sub_u32_e32 v20, v20, v21
	v_exp_f32_e32 v0, v0
	v_cvt_f32_u32_e32 v20, v20
	v_pk_mul_f32 v[176:177], v[2:3], v[18:19]
	v_cndmask_b32_e32 v2, 0, v188, vcc
	v_ldexp_f32 v2, v0, v2
	v_mul_f32_e32 v0, v194, v20
	v_cmp_gt_f32_e32 vcc, s34, v0
	v_or_b32_e32 v3, 40, v171
	v_min_u32_e32 v18, v3, v193
	v_cndmask_b32_e32 v0, 0, v187, vcc
	v_fmac_f32_e32 v0, v194, v20
	v_exp_f32_e32 v0, v0
	v_max_u32_e32 v3, v3, v193
	v_sub_u32_e32 v3, v3, v18
	v_cvt_f32_u32_e32 v18, v3
	v_cndmask_b32_e32 v3, 0, v188, vcc
	v_ldexp_f32 v3, v0, v3
	v_pk_mul_f32 v[178:179], v[4:5], v[2:3]
	v_or_b32_e32 v2, 41, v171
	v_min_u32_e32 v3, v2, v193
	v_max_u32_e32 v2, v2, v193
	v_sub_u32_e32 v2, v2, v3
	v_cvt_f32_u32_e32 v2, v2
	v_mul_f32_e32 v0, v194, v18
	v_cmp_gt_f32_e32 vcc, s34, v0
	v_cvt_pk_bf16_f32 v131, v152, v153
	v_mul_f32_e32 v4, v194, v2
	v_cndmask_b32_e32 v0, 0, v187, vcc
	v_cndmask_b32_e32 v3, 0, v188, vcc
	v_cmp_gt_f32_e32 vcc, s34, v4
	v_fmac_f32_e32 v0, v194, v18
	v_exp_f32_e32 v0, v0
	v_cndmask_b32_e32 v4, 0, v187, vcc
	v_fmac_f32_e32 v4, v194, v2
	v_or_b32_e32 v2, 42, v171
	v_min_u32_e32 v5, v2, v193
	v_max_u32_e32 v2, v2, v193
	v_sub_u32_e32 v2, v2, v5
	v_exp_f32_e32 v4, v4
	v_cvt_f32_u32_e32 v5, v2
	v_ldexp_f32 v2, v0, v3
	v_cndmask_b32_e32 v0, 0, v188, vcc
	v_ldexp_f32 v3, v4, v0
	v_mul_f32_e32 v0, v194, v5
	v_cmp_gt_f32_e32 vcc, s34, v0
	v_or_b32_e32 v4, 43, v171
	v_pk_mul_f32 v[6:7], v[6:7], v[2:3]
	v_cndmask_b32_e32 v0, 0, v187, vcc
	v_fmac_f32_e32 v0, v194, v5
	v_min_u32_e32 v5, v4, v193
	v_max_u32_e32 v4, v4, v193
	v_sub_u32_e32 v4, v4, v5
	v_exp_f32_e32 v0, v0
	v_cvt_f32_u32_e32 v4, v4
	v_cndmask_b32_e32 v2, 0, v188, vcc
	v_or_b32_e32 v3, 48, v171
	v_ldexp_f32 v2, v0, v2
	v_mul_f32_e32 v0, v194, v4
	v_cmp_gt_f32_e32 vcc, s34, v0
	v_cvt_pk_bf16_f32 v132, v156, v157
	v_cvt_pk_bf16_f32 v133, v158, v159
	v_cndmask_b32_e32 v0, 0, v187, vcc
	v_fmac_f32_e32 v0, v194, v4
	v_exp_f32_e32 v0, v0
	v_min_u32_e32 v4, v3, v193
	v_max_u32_e32 v3, v3, v193
	v_sub_u32_e32 v3, v3, v4
	v_cvt_f32_u32_e32 v4, v3
	v_cndmask_b32_e32 v3, 0, v188, vcc
	v_ldexp_f32 v3, v0, v3
	v_pk_mul_f32 v[8:9], v[8:9], v[2:3]
	v_or_b32_e32 v2, 49, v171
	v_min_u32_e32 v3, v2, v193
	v_max_u32_e32 v2, v2, v193
	v_sub_u32_e32 v2, v2, v3
	v_cvt_f32_u32_e32 v2, v2
	v_mul_f32_e32 v0, v194, v4
	v_cmp_gt_f32_e32 vcc, s34, v0
	v_cvt_pk_bf16_f32 v126, v160, v161
	s_nop 0
	v_cndmask_b32_e32 v0, 0, v187, vcc
	v_fmac_f32_e32 v0, v194, v4
	v_mul_f32_e32 v4, v194, v2
	v_cndmask_b32_e32 v3, 0, v188, vcc
	v_cmp_gt_f32_e32 vcc, s34, v4
	v_exp_f32_e32 v0, v0
	s_nop 0
	v_cndmask_b32_e32 v4, 0, v187, vcc
	v_fmac_f32_e32 v4, v194, v2
	v_or_b32_e32 v2, 50, v171
	v_min_u32_e32 v5, v2, v193
	v_max_u32_e32 v2, v2, v193
	v_sub_u32_e32 v2, v2, v5
	v_exp_f32_e32 v4, v4
	v_cvt_f32_u32_e32 v5, v2
	v_ldexp_f32 v2, v0, v3
	v_cndmask_b32_e32 v0, 0, v188, vcc
	v_ldexp_f32 v3, v4, v0
	v_mul_f32_e32 v0, v194, v5
	v_cmp_gt_f32_e32 vcc, s34, v0
	v_or_b32_e32 v4, 51, v171
	v_pk_mul_f32 v[10:11], v[10:11], v[2:3]
	v_cndmask_b32_e32 v0, 0, v187, vcc
	v_fmac_f32_e32 v0, v194, v5
	v_exp_f32_e32 v0, v0
	v_min_u32_e32 v5, v4, v193
	v_max_u32_e32 v4, v4, v193
	v_cndmask_b32_e32 v2, 0, v188, vcc
	v_sub_u32_e32 v4, v4, v5
	v_ldexp_f32 v18, v0, v2
	v_or_b32_e32 v2, 56, v171
	v_cvt_f32_u32_e32 v4, v4
	v_min_u32_e32 v3, v2, v193
	v_max_u32_e32 v2, v2, v193
	v_sub_u32_e32 v2, v2, v3
	v_cvt_f32_u32_e32 v22, v2
	v_or_b32_e32 v2, v192, v195
	v_ashrrev_i32_e32 v3, 31, v2
	v_mul_f32_e32 v0, v194, v4
	v_lshlrev_b64 v[2:3], 8, v[2:3]
	v_cmp_gt_f32_e32 vcc, s34, v0
	v_lshl_add_u64 v[2:3], v[154:155], 0, v[2:3]
	v_lshl_add_u64 v[20:21], v[2:3], 0, v[32:33]
	v_cndmask_b32_e32 v0, 0, v187, vcc
	v_fmac_f32_e32 v0, v194, v4
	ds_read_b128 v[2:5], v233 offset:8704
	ds_read_b128 v[158:161], v233 offset:8736
	ds_read_b128 v[154:157], v233 offset:8768
	ds_read_b128 v[150:153], v233 offset:8800
	ds_read_b128 v[146:149], v233 offset:8832
	ds_read_b128 v[142:145], v233 offset:8864
	ds_read_b128 v[138:141], v233 offset:8896
	ds_read_b128 v[134:137], v233 offset:8928
	v_exp_f32_e32 v0, v0
	v_cndmask_b32_e32 v19, 0, v188, vcc
	v_ldexp_f32 v19, v0, v19
	v_mul_f32_e32 v0, v194, v22
	v_cmp_gt_f32_e32 vcc, s34, v0
	v_pk_mul_f32 v[12:13], v[12:13], v[18:19]
	v_or_b32_e32 v18, 57, v171
	v_cndmask_b32_e32 v0, 0, v187, vcc
	v_fmac_f32_e32 v0, v194, v22
	v_exp_f32_e32 v0, v0
	v_min_u32_e32 v19, v18, v193
	v_max_u32_e32 v18, v18, v193
	v_sub_u32_e32 v18, v18, v19
	v_cvt_f32_u32_e32 v195, v18
	v_cndmask_b32_e32 v18, 0, v188, vcc
	v_ldexp_f32 v196, v0, v18
	s_waitcnt lgkmcnt(8)
	v_mfma_f32_32x32x16_bf16 v[18:33], v[24:27], v[78:81], 0
	v_mul_f32_e32 v0, v194, v195
	v_cmp_gt_f32_e32 vcc, s34, v0
	s_nop 1
	v_cndmask_b32_e32 v0, 0, v187, vcc
	v_fmac_f32_e32 v0, v194, v195
	v_or_b32_e32 v195, 58, v171
	s_nop 0
	v_mfma_f32_32x32x16_bf16 v[18:33], v[122:125], v[74:77], v[18:33]
	v_min_u32_e32 v197, v195, v193
	v_max_u32_e32 v122, v195, v193
	v_sub_u32_e32 v122, v122, v197
	v_exp_f32_e32 v0, v0
	v_cvt_f32_u32_e32 v122, v122
	v_cndmask_b32_e32 v123, 0, v188, vcc
	v_ldexp_f32 v197, v0, v123
	s_nop 0
	v_mfma_f32_32x32x16_bf16 v[18:33], v[118:121], v[70:73], v[18:33]
	v_or_b32_e32 v118, 59, v171
	v_min_u32_e32 v119, v118, v193
	v_max_u32_e32 v118, v118, v193
	v_sub_u32_e32 v118, v118, v119
	v_cvt_f32_u32_e32 v118, v118
	v_mul_f32_e32 v0, v194, v122
	v_cmp_gt_f32_e32 vcc, s34, v0
	s_nop 0
	v_mfma_f32_32x32x16_bf16 v[18:33], v[114:117], v[66:69], v[18:33]
	v_mul_f32_e32 v114, v194, v118
	v_cndmask_b32_e32 v0, 0, v187, vcc
	v_cmp_gt_f32_e64 s[0:1], s34, v114
	v_fmac_f32_e32 v0, v194, v122
	v_exp_f32_e32 v0, v0
	v_cndmask_b32_e64 v114, 0, v187, s[0:1]
	v_fmac_f32_e32 v114, v194, v118
	s_nop 0
	v_mfma_f32_32x32x16_bf16 v[18:33], v[110:113], v[62:65], v[18:33]
	v_exp_f32_e32 v114, v114
	v_cndmask_b32_e32 v110, 0, v188, vcc
	v_ldexp_f32 v110, v0, v110
	v_cndmask_b32_e64 v0, 0, v188, s[0:1]
	v_ldexp_f32 v111, v114, v0
	v_add_u32_e32 v0, 1, v193
	v_cvt_f32_u32_e32 v0, v0
	s_nop 0
	v_mfma_f32_32x32x16_bf16 v[18:33], v[46:49], v[58:61], v[18:33]
	v_cvt_pk_bf16_f32 v116, v6, v7
	v_mul_f32_e64 v14, v14, v196
	v_mul_f32_e64 v15, v15, v197
	v_mul_f32_e32 v6, v194, v0
	v_cmp_gt_f32_e32 vcc, s34, v6
	v_pk_mul_f32 v[16:17], v[16:17], v[110:111]
	v_cvt_pk_bf16_f32 v114, v176, v177
	v_cndmask_b32_e32 v6, 0, v187, vcc
	s_nop 0
	v_mfma_f32_32x32x16_bf16 v[18:33], v[42:45], v[54:57], v[18:33]
	v_fmac_f32_e32 v6, v194, v0
	v_exp_f32_e32 v0, v6
	v_cndmask_b32_e32 v6, 0, v188, vcc
	v_cvt_pk_bf16_f32 v115, v178, v179
	v_cvt_pk_bf16_f32 v117, v8, v9
	v_ldexp_f32 v0, v0, v6
	v_cvt_pk_bf16_f32 v110, v10, v11
	s_nop 0
	v_mfma_f32_32x32x16_bf16 v[18:33], v[38:41], v[50:53], v[18:33]
	v_cvt_pk_bf16_f32 v111, v12, v13
	v_cvt_pk_bf16_f32 v112, v14, v15
	v_cvt_pk_bf16_f32 v113, v16, v17
	s_waitcnt lgkmcnt(7)
	v_mfma_f32_32x32x16_bf16 v[2:17], v[2:5], v[78:81], 0
	s_movk_i32 s0, 0xffe0
	v_cmp_eq_u32_e32 vcc, 0, v173
	s_barrier
	s_waitcnt lgkmcnt(6)
	v_mfma_f32_32x32x16_bf16 v[2:17], v[158:161], v[74:77], v[2:17]
	s_waitcnt lgkmcnt(5)
	v_mfma_f32_32x32x16_bf16 v[2:17], v[154:157], v[70:73], v[2:17]
	s_waitcnt lgkmcnt(4)
	v_mfma_f32_32x32x16_bf16 v[2:17], v[150:153], v[66:69], v[2:17]
	s_waitcnt lgkmcnt(3)
	v_mfma_f32_32x32x16_bf16 v[2:17], v[146:149], v[62:65], v[2:17]
	s_waitcnt lgkmcnt(2)
	v_mfma_f32_32x32x16_bf16 v[2:17], v[142:145], v[58:61], v[2:17]
	s_waitcnt lgkmcnt(1)
	v_mfma_f32_32x32x16_bf16 v[2:17], v[138:141], v[54:57], v[2:17]
	v_mfma_f32_32x32x16_bf16 v[34:49], v[34:37], v[130:133], 0
	s_waitcnt lgkmcnt(0)
	v_mfma_f32_32x32x16_bf16 v[2:17], v[134:137], v[50:53], v[2:17]
	v_mfma_f32_32x32x16_bf16 v[50:65], v[94:97], v[130:133], 0
	v_mfma_f32_32x32x16_bf16 v[34:49], v[106:109], v[126:129], v[34:49]
	v_mfma_f32_32x32x16_bf16 v[50:65], v[90:93], v[126:129], v[50:65]
	v_mfma_f32_32x32x16_bf16 v[34:49], v[102:105], v[114:117], v[34:49]
	v_mfma_f32_32x32x16_bf16 v[50:65], v[86:89], v[114:117], v[50:65]
	v_mfma_f32_32x32x16_bf16 v[34:49], v[98:101], v[110:113], v[34:49]
	v_mfma_f32_32x32x16_bf16 v[50:65], v[82:85], v[110:113], v[50:65]
	s_nop 10
	v_fma_f32 v66, v0, v18, v34
	v_fma_f32 v67, v0, v19, v35
	v_fma_f32 v68, v0, v20, v36
	v_fma_f32 v69, v0, v21, v37
	v_fma_f32 v70, v0, v22, v38
	v_fma_f32 v71, v0, v23, v39
	v_pk_fma_f32 v[38:39], v[0:1], v[24:25], v[40:41] op_sel_hi:[0,1,1]
	v_pk_fma_f32 v[24:25], v[0:1], v[30:31], v[46:47] op_sel_hi:[0,1,1]
	v_pk_mul_f32 v[30:31], v[66:67], v[66:67]
	v_pk_fma_f32 v[36:37], v[0:1], v[26:27], v[42:43] op_sel_hi:[0,1,1]
	v_pk_fma_f32 v[34:35], v[0:1], v[28:29], v[44:45] op_sel_hi:[0,1,1]
	v_pk_fma_f32 v[22:23], v[0:1], v[32:33], v[48:49] op_sel_hi:[0,1,1]
	v_pk_mul_f32 v[32:33], v[68:69], v[68:69]
	v_pk_fma_f32 v[28:29], v[0:1], v[2:3], v[50:51] op_sel_hi:[0,1,1]
	v_pk_fma_f32 v[26:27], v[0:1], v[4:5], v[52:53] op_sel_hi:[0,1,1]
	v_pk_fma_f32 v[20:21], v[0:1], v[6:7], v[54:55] op_sel_hi:[0,1,1]
	v_pk_fma_f32 v[18:19], v[0:1], v[8:9], v[56:57] op_sel_hi:[0,1,1]
	v_pk_fma_f32 v[8:9], v[0:1], v[10:11], v[58:59] op_sel_hi:[0,1,1]
	v_pk_fma_f32 v[6:7], v[0:1], v[12:13], v[60:61] op_sel_hi:[0,1,1]
	v_pk_fma_f32 v[4:5], v[0:1], v[14:15], v[62:63] op_sel_hi:[0,1,1]
	v_pk_fma_f32 v[2:3], v[0:1], v[16:17], v[64:65] op_sel_hi:[0,1,1]
	v_add_f32_e32 v0, v30, v31
	v_add_f32_e32 v0, v32, v0
	v_pk_mul_f32 v[40:41], v[70:71], v[70:71]
	v_add_f32_e32 v0, v33, v0
	v_add_f32_e32 v0, v40, v0
	v_pk_mul_f32 v[42:43], v[38:39], v[38:39]
	v_add_f32_e32 v0, v41, v0
	v_add_f32_e32 v0, v42, v0
	v_pk_mul_f32 v[44:45], v[36:37], v[36:37]
	v_add_f32_e32 v0, v43, v0
	v_add_f32_e32 v0, v44, v0
	v_pk_mul_f32 v[46:47], v[34:35], v[34:35]
	v_add_f32_e32 v0, v45, v0
	v_add_f32_e32 v0, v46, v0
	v_pk_mul_f32 v[48:49], v[24:25], v[24:25]
	v_add_f32_e32 v0, v47, v0
	v_add_f32_e32 v0, v48, v0
	v_pk_mul_f32 v[72:73], v[22:23], v[22:23]
	v_add_f32_e32 v0, v49, v0
	v_add_f32_e32 v0, v72, v0
	v_pk_mul_f32 v[50:51], v[28:29], v[28:29]
	v_add_f32_e32 v0, v73, v0
	v_add_f32_e32 v0, v50, v0
	v_pk_mul_f32 v[52:53], v[26:27], v[26:27]
	v_add_f32_e32 v0, v51, v0
	v_add_f32_e32 v0, v52, v0
	v_pk_mul_f32 v[54:55], v[20:21], v[20:21]
	v_add_f32_e32 v0, v53, v0
	v_add_f32_e32 v0, v54, v0
	v_pk_mul_f32 v[56:57], v[18:19], v[18:19]
	v_add_f32_e32 v0, v55, v0
	v_add_f32_e32 v0, v56, v0
	v_pk_mul_f32 v[10:11], v[8:9], v[8:9]
	v_add_f32_e32 v0, v57, v0
	v_add_f32_e32 v0, v10, v0
	v_pk_mul_f32 v[12:13], v[6:7], v[6:7]
	v_add_f32_e32 v0, v11, v0
	v_add_f32_e32 v0, v12, v0
	v_pk_mul_f32 v[14:15], v[4:5], v[4:5]
	v_add_f32_e32 v0, v13, v0
	v_add_f32_e32 v0, v14, v0
	v_pk_mul_f32 v[16:17], v[2:3], v[2:3]
	v_add_f32_e32 v0, v15, v0
	v_add_f32_e32 v0, v16, v0
	v_add_f32_e32 v0, v17, v0
	ds_bpermute_b32 v12, v234, v0
	v_bfi_b32 v10, s0, v191, v172
	v_lshl_add_u32 v11, v10, 2, v182
	s_and_saveexec_b64 s[0:1], vcc
	s_cbranch_execz .LBB0_871
	s_waitcnt lgkmcnt(0)
	v_add_f32_e32 v0, v0, v12
	ds_write_b32 v11, v0
	s_branch .LBB0_871
